# stack plus rnn pass 1 store addresses: token terms pre-shifted once, one 64-bit add per store
# speedup vs baseline: 1.0089x; 1.0050x over previous
; #define LAS __attribute__((address_space(3)))
; DI float sigm(float x) { return __builtin_amdgcn_rcpf(1.0f + __builtin_amdgcn_exp2f(-x * LOG2E)); }
; DI void rnn_phase(LAS unsigned char* lds, bf16_t* P, const bf16_t* WaT, const bf16_t* WiT, const float* convw, const float* convb, const float* ba, const float* bi, const float* lam,
;                   f32x2* sums, unsigned* au, bool fin, int bx, int G, int tid, int wid, int lane) {
;     ...
;     LAS float* XC = (LAS float*)lds; LAS float* AA = (LAS float*)(lds + 32768); LAS bf16_t* XB = (LAS bf16_t*)(lds + 65536); LAS bf16_t* WL = (LAS bf16_t*)(lds + 83968);
;     LAS float* SG = (LAS float*)(lds + 102400); LAS float* PF = (LAS float*)(lds + 106496); LAS float* CW = (LAS float*)(lds + 110592);
;     const int t = tid >> 2, cq = tid & 3;
;     const int tt = wid >> 1, nt = wid & 1, l32 = lane & 31, hl = lane >> 5;
;     ...
;             const int ch = 32 * nt + l32;
;             float At = 1.f, Ht = 0.f;
; #pragma unroll
;             for (int g = 0; g < 4; ++g) {
;                 float A = 1.f, H = 0.f;
; #pragma unroll
;                 for (int q4 = 0; q4 < 4; ++q4) { const int i = 4 * g + q4, tok = 32 * tt + 8 * g + 4 * hl + q4;
;                     const float r = sigm(aR[i] + bac), ig = sigm(aI[i] + bic);
;                     const float a = __builtin_amdgcn_exp2f(k8c * r);
;                     const float uu_ = __builtin_amdgcn_sqrtf(fmaxf(1.0f - a * a, 0.f)) * ig * XC[tok * 64 + ch];
;                     { const h2_t pv = {(_Float16)(1.0f - a), (_Float16)uu_}; au[(rowbase + tok) * D + ch0 + ch] = __builtin_bit_cast(unsigned, pv); }
.LBB0_340:
	s_or_b64 exec, exec, s[36:37]
	s_ashr_i32 s1, s0, 31
	s_mul_i32 s19, s0, 0x27c0000
	s_mul_hi_i32 s12, s0, 0x27c0000
	s_add_u32 s20, s30, s19
	s_addc_u32 s21, s31, s12
	s_lshl_b64 s[22:23], s[0:1], 14
	v_readlane_b32 s36, v235, 38
	v_readlane_b32 s37, v235, 39
	s_add_u32 s46, s36, s22
	s_addc_u32 s47, s37, s23
	s_lshl_b32 s0, s0, 10
	s_ashr_i32 s1, s0, 31
	v_readlane_b32 s38, v235, 40
	s_lshl_b64 s[0:1], s[0:1], 2
	v_readlane_b32 s39, v235, 41
	s_add_u32 s48, s38, s0
	s_addc_u32 s49, s39, s1
	v_readlane_b32 s22, v235, 30
	v_readlane_b32 s23, v235, 31
	s_add_u32 s50, s22, s0
	s_addc_u32 s51, s23, s1
	v_readlane_b32 s36, v235, 42
	v_readlane_b32 s37, v235, 43
	s_add_u32 s52, s36, s0
	v_readlane_b32 s38, v235, 44
	s_addc_u32 s53, s37, s1
	v_ashrrev_i32_e32 v5, 3, v65
	v_readlane_b32 s39, v235, 45
	s_add_u32 s54, s38, s0
	v_lshlrev_b32_e32 v0, 6, v5
	s_addc_u32 s55, s39, s1
	s_ashr_i32 s12, s18, 7
	v_ashrrev_i32_e32 v1, 31, v0
	v_lshlrev_b32_e32 v6, 4, v65
	s_movk_i32 s18, 0xff
	v_and_b32_e32 v80, 0x70, v6
	v_lshl_add_u64 v[0:1], v[0:1], 1, s[20:21]
	v_cmp_lt_i32_e64 s[36:37], s18, v65
	s_movk_i32 s18, 0xfc00
	v_lshl_add_u64 v[0:1], v[0:1], 0, v[80:81]
	s_mov_b64 s[0:1], 0x2a80000
	v_and_or_b32 v116, v6, s18, v64
	v_readlane_b32 s18, v235, 24
	v_and_b32_e32 v3, 31, v65
	v_lshl_add_u64 v[70:71], v[0:1], 0, s[0:1]
	s_movk_i32 s19, 0x90
	s_mov_b64 s[0:1], 0x2aa0000
	v_lshl_add_u32 v117, v65, 2, s18
	s_lshl_b32 s18, s7, 5
	v_lshl_add_u64 v[72:73], v[0:1], 0, s[0:1]
	v_and_or_b32 v74, s18, 32, v3
	v_mul_lo_u32 v1, v66, s19
	s_lshl_b32 s18, s12, 5
	v_lshrrev_b32_e32 v4, 5, v64
	v_add3_u32 v119, s91, v1, v68
	v_or_b32_e32 v1, s18, v3
	v_lshlrev_b32_e32 v118, 6, v2
	v_mul_lo_u32 v1, v1, s19
	v_lshlrev_b32_e32 v2, 4, v4
	v_add3_u32 v120, s91, v1, v2
	v_mul_u32_u24_e32 v1, 0x48, v74
	v_readlane_b32 s20, v235, 22
	v_readlane_b32 s21, v235, 23
	v_lshlrev_b32_e32 v1, 1, v1
	v_add3_u32 v121, s20, v1, v2
	v_add3_u32 v122, s21, v1, v2
	v_lshl_or_b32 v76, v4, 2, s18
	v_xor_b32_e32 v2, 32, v164
	s_lshl_b32 s18, s12, 8
	v_readlane_b32 s22, v235, 25
	v_mul_lo_u32 v5, v5, s19
	v_cmp_lt_i32_e32 vcc, v2, v165
	s_add_i32 s18, s22, s18
	v_add3_u32 v114, s20, v5, v80
	v_add3_u32 v115, s21, v5, v80
	v_lshlrev_b32_e32 v80, 2, v74
	v_cndmask_b32_e32 v2, v164, v2, vcc
	s_cmp_eq_u32 s12, 3
	v_or_b32_e32 v84, 1, v76
	v_or_b32_e32 v86, 2, v76
	v_or_b32_e32 v88, 3, v76
	v_or_b32_e32 v90, 8, v76
	v_or_b32_e32 v92, 9, v76
	v_or_b32_e32 v94, 10, v76
	v_or_b32_e32 v96, 11, v76
	v_or_b32_e32 v98, 16, v76
	v_or_b32_e32 v100, 17, v76
	v_or_b32_e32 v102, 18, v76
	v_or_b32_e32 v104, 19, v76
	v_or_b32_e32 v106, 24, v76
	v_or_b32_e32 v108, 25, v76
	v_or_b32_e32 v110, 26, v76
	v_or_b32_e32 v112, 27, v76
	s_movk_i32 s0, 0x140
	v_lshl_add_u32 v0, v66, 8, 0
	v_add_u32_e32 v1, 0, v80
	v_lshlrev_b32_e32 v123, 2, v2
	v_cmp_gt_u32_e64 s[40:41], 32, v64
	s_cselect_b64 s[20:21], -1, 0
	v_lshlrev_b32_e32 v2, 8, v76
	v_lshlrev_b32_e32 v3, 8, v84
	v_lshlrev_b32_e32 v4, 8, v86
	v_lshlrev_b32_e32 v5, 8, v88
	v_lshlrev_b32_e32 v6, 8, v90
	v_lshlrev_b32_e32 v7, 8, v92
	v_lshlrev_b32_e32 v8, 8, v94
	v_lshlrev_b32_e32 v9, 8, v96
	v_lshlrev_b32_e32 v10, 8, v98
	v_lshlrev_b32_e32 v11, 8, v100
	v_lshlrev_b32_e32 v12, 8, v102
	v_lshlrev_b32_e32 v13, 8, v104
	v_lshlrev_b32_e32 v14, 8, v106
	v_lshlrev_b32_e32 v15, 8, v108
	v_lshlrev_b32_e32 v16, 8, v110
	v_lshlrev_b32_e32 v17, 8, v112
	v_cmp_gt_i32_e64 s[0:1], s0, v65
	v_lshl_add_u64 v[78:79], s[44:45], 0, v[80:81]
	s_mov_b32 s19, -1
	v_add_u32_e32 v124, s18, v80
	s_and_b64 s[56:57], s[40:41], s[20:21]
	v_add_u32_e32 v125, s22, v80
	v_ashrrev_i32_e32 v77, 31, v76
	v_ashrrev_i32_e32 v85, 31, v84
	v_ashrrev_i32_e32 v87, 31, v86
	v_ashrrev_i32_e32 v89, 31, v88
	v_ashrrev_i32_e32 v91, 31, v90
	v_ashrrev_i32_e32 v93, 31, v92
	v_ashrrev_i32_e32 v95, 31, v94
	v_ashrrev_i32_e32 v97, 31, v96
	v_ashrrev_i32_e32 v99, 31, v98
	v_ashrrev_i32_e32 v101, 31, v100
	v_ashrrev_i32_e32 v103, 31, v102
	v_ashrrev_i32_e32 v105, 31, v104
	v_ashrrev_i32_e32 v107, 31, v106
	v_ashrrev_i32_e32 v109, 31, v108
	v_ashrrev_i32_e32 v111, 31, v110
	v_ashrrev_i32_e32 v113, 31, v112
	v_add_u32_e32 v126, v0, v118
	v_add_u32_e32 v127, v1, v2
	v_add_u32_e32 v128, v1, v3
	v_add_u32_e32 v129, v1, v4
	v_add_u32_e32 v130, v1, v5
	v_add_u32_e32 v131, v1, v6
	v_add_u32_e32 v132, v1, v7
	v_add_u32_e32 v133, v1, v8
	v_add_u32_e32 v134, v1, v9
	v_add_u32_e32 v135, v1, v10
	v_add_u32_e32 v136, v1, v11
	v_add_u32_e32 v137, v1, v12
	v_add_u32_e32 v138, v1, v13
	v_add_u32_e32 v139, v1, v14
	v_add_u32_e32 v140, v1, v15
	v_add_u32_e32 v141, v1, v16
	v_add_u32_e32 v142, v1, v17
	v_readlane_b32 s25, v235, 18
	v_readlane_b32 s62, v235, 17
	v_mov_b32_e32 v143, 0
	v_mov_b32_e32 v144, 0
	s_mov_b32 s18, s28
	v_lshlrev_b64 v[176:177], 12, v[76:77]
	v_lshlrev_b64 v[178:179], 12, v[84:85]
	v_lshlrev_b64 v[180:181], 12, v[86:87]
	v_lshlrev_b64 v[182:183], 12, v[88:89]
	v_lshlrev_b64 v[184:185], 12, v[90:91]
	v_lshlrev_b64 v[186:187], 12, v[92:93]
	v_lshlrev_b64 v[188:189], 12, v[94:95]
	v_lshlrev_b64 v[190:191], 12, v[96:97]
	v_lshlrev_b64 v[192:193], 12, v[98:99]
	v_lshlrev_b64 v[194:195], 12, v[100:101]
	v_lshlrev_b64 v[196:197], 12, v[102:103]
	v_lshlrev_b64 v[198:199], 12, v[104:105]
	v_lshlrev_b64 v[200:201], 12, v[106:107]
	v_lshlrev_b64 v[202:203], 12, v[108:109]
	v_lshlrev_b64 v[204:205], 12, v[110:111]
	v_lshlrev_b64 v[206:207], 12, v[112:113]
	s_branch .LBB0_342

; #define LAS __attribute__((address_space(3)))
; DI float sigm(float x) { return __builtin_amdgcn_rcpf(1.0f + __builtin_amdgcn_exp2f(-x * LOG2E)); }
; #define MFMA32(a, b, c) __builtin_amdgcn_mfma_f32_32x32x16_bf16((a), (b), (c), 0, 0, 0)
; DI void rnn_phase(LAS unsigned char* lds, bf16_t* P, const bf16_t* WaT, const bf16_t* WiT, const float* convw, const float* convb, const float* ba, const float* bi, const float* lam,
;                   f32x2* sums, unsigned* au, bool fin, int bx, int G, int tid, int wid, int lane) {
;     ...
;             f32x16 aR, aI;
; #pragma unroll
;             for (int i = 0; i < 16; ++i) { aR[i] = 0.f; aI[i] = 0.f; }
; #pragma unroll
;             for (int s = 0; s < 4; ++s) {
;                 const bf16x8 af = *(const LAS bf16x8*)(XB + (32 * tt + l32) * 72 + 16 * s + 8 * hl);
;                 const bf16x8 bR = *(const LAS bf16x8*)(WL + (32 * nt + l32) * 72 + 16 * s + 8 * hl);
;                 const bf16x8 bI = *(const LAS bf16x8*)(WL + 64 * 72 + (32 * nt + l32) * 72 + 16 * s + 8 * hl);
;                 aR = MFMA32(af, bR, aR); aI = MFMA32(af, bI, aI);
;             }
;             const int ch = 32 * nt + l32;
;             float At = 1.f, Ht = 0.f;
; #pragma unroll
;             for (int g = 0; g < 4; ++g) {
;                 float A = 1.f, H = 0.f;
; #pragma unroll
;                 for (int q4 = 0; q4 < 4; ++q4) { const int i = 4 * g + q4, tok = 32 * tt + 8 * g + 4 * hl + q4;
;                     const float r = sigm(aR[i] + bac), ig = sigm(aI[i] + bic);
;                     const float a = __builtin_amdgcn_exp2f(k8c * r);
;                     const float uu_ = __builtin_amdgcn_sqrtf(fmaxf(1.0f - a * a, 0.f)) * ig * XC[tok * 64 + ch];
;                     { const h2_t pv = {(_Float16)(1.0f - a), (_Float16)uu_}; au[(rowbase + tok) * D + ch0 + ch] = __builtin_bit_cast(unsigned, pv); }
.LBB0_360:
	s_waitcnt lgkmcnt(0)
	s_barrier
	ds_read_b128 v[0:3], v120
	ds_read_b128 v[4:7], v121
	s_ashr_i32 s58, s18, 10
	s_waitcnt lgkmcnt(0)
	v_mfma_f32_32x32x16_bf16 v[16:31], v[0:3], v[4:7], 0
	ds_read_b128 v[4:7], v122
	ds_read_b128 v[150:153], v120 offset:32
	ds_read_b128 v[154:157], v121 offset:32
	s_bfe_u32 s21, s18, 0x60004
	s_ashr_i32 s59, s58, 31
	s_lshl_b64 s[60:61], s[58:59], 13
	s_lshl_b32 s12, s21, 7
	s_or_b32 s60, s60, s12
	s_waitcnt lgkmcnt(0)
	v_mfma_f32_32x32x16_bf16 v[0:15], v[0:3], v[4:7], 0
	s_lshl_b32 s88, s63, 2
	v_lshl_add_u64 v[82:83], v[78:79], 0, s[88:89]
	v_mov_b64_e32 v[208:209], s[60:61]
	v_lshlrev_b64 v[208:209], 12, v[208:209]
	v_lshl_add_u64 v[208:209], v[82:83], 0, v[208:209]
	v_mfma_f32_32x32x16_bf16 v[16:31], v[150:153], v[154:157], v[16:31]
	ds_read_b128 v[154:157], v122 offset:32
	s_waitcnt lgkmcnt(0)
	v_mfma_f32_32x32x16_bf16 v[0:15], v[150:153], v[154:157], v[0:15]
	ds_read_b128 v[150:153], v120 offset:64
	ds_read_b128 v[154:157], v121 offset:64
	s_waitcnt lgkmcnt(0)
	v_mfma_f32_32x32x16_bf16 v[16:31], v[150:153], v[154:157], v[16:31]
	ds_read_b128 v[154:157], v120 offset:96
	ds_read_b128 v[158:161], v121 offset:96
	ds_read_b128 v[172:175], v122 offset:96
	s_waitcnt lgkmcnt(0)
	v_mfma_f32_32x32x16_bf16 v[16:31], v[154:157], v[158:161], v[16:31]
	ds_read_b128 v[158:161], v122 offset:64
	s_waitcnt lgkmcnt(0)
	v_mfma_f32_32x32x16_bf16 v[0:15], v[150:153], v[158:161], v[0:15]
	s_nop 8
	v_add_f32_e32 v16, v75, v16
	v_mul_f32_e32 v16, 0xbfb8aa3b, v16
	v_exp_f32_e32 v16, v16
	v_add_f32_e32 v17, v75, v17
	v_mul_f32_e32 v17, 0xbfb8aa3b, v17
	v_exp_f32_e32 v80, v17
	v_add_f32_e32 v16, 1.0, v16
	v_mfma_f32_32x32x16_bf16 v[0:15], v[154:157], v[172:175], v[0:15]
	v_rcp_f32_e32 v16, v16
	v_add_f32_e32 v80, 1.0, v80
	v_rcp_f32_e32 v80, v80
	ds_read_b32 v147, v127
	ds_read_b32 v149, v128
	ds_read_b32 v150, v129
	ds_read_b32 v151, v130
	ds_read_b32 v152, v131
	ds_read_b32 v153, v132
	ds_read_b32 v154, v133
	ds_read_b32 v155, v134
	v_mul_f32_e32 v16, v144, v16
	v_exp_f32_e32 v69, v16
	v_add_f32_e32 v0, v143, v0
	v_mul_f32_e32 v0, 0xbfb8aa3b, v0
	v_exp_f32_e32 v0, v0
	v_fma_f32 v16, -v69, v69, 1.0
	v_max_f32_e32 v16, 0, v16
	v_sqrt_f32_e32 v145, v16
	v_add_f32_e32 v0, 1.0, v0
	v_rcp_f32_e32 v0, v0
	v_add_f32_e32 v1, v143, v1
	v_mul_f32_e32 v1, 0xbfb8aa3b, v1
	v_mul_f32_e32 v0, v0, v145
	s_waitcnt lgkmcnt(0)
	v_mul_f32_e32 v145, v147, v0
	v_mul_f32_e32 v0, v144, v80
	v_exp_f32_e32 v80, v0
	v_exp_f32_e32 v147, v1
	v_sub_f32_e32 v146, 1.0, v69
	v_fma_f32 v17, -v80, v80, 1.0
	v_add_f32_e32 v16, 1.0, v147
	v_max_f32_e32 v17, 0, v17
	v_rcp_f32_e32 v16, v16
	v_sqrt_f32_e32 v17, v17
	v_cvt_pk_f16_f32 v146, v146, v145
	v_lshl_add_u64 v[0:1], v[176:177], 0, v[208:209]
	global_store_dword v[0:1], v146, off
	v_add_f32_e32 v1, v75, v18
	v_mul_f32_e32 v1, 0xbfb8aa3b, v1
	v_mul_f32_e32 v0, v16, v17
	v_exp_f32_e32 v17, v1
	v_add_f32_e32 v2, v143, v2
	v_mul_f32_e32 v2, 0xbfb8aa3b, v2
	v_exp_f32_e32 v2, v2
	v_add_f32_e32 v17, 1.0, v17
	v_rcp_f32_e32 v17, v17
	v_mul_f32_e32 v16, v149, v0
	v_sub_f32_e32 v0, 1.0, v80
	v_cvt_pk_f16_f32 v18, v0, v16
	v_mul_f32_e32 v17, v144, v17
	v_exp_f32_e32 v17, v17
	v_add_f32_e32 v2, 1.0, v2
	v_fma_f32 v146, -v17, v17, 1.0
	v_max_f32_e32 v146, 0, v146
	v_rcp_f32_e32 v2, v2
	v_sqrt_f32_e32 v146, v146
	v_lshl_add_u64 v[0:1], v[178:179], 0, v[208:209]
	global_store_dword v[0:1], v18, off
	v_add_f32_e32 v1, v75, v19
	v_mul_f32_e32 v1, 0xbfb8aa3b, v1
	v_mul_f32_e32 v0, v2, v146
	v_exp_f32_e32 v2, v1
	v_add_f32_e32 v3, v143, v3
	v_fmac_f32_e32 v145, 0, v69
	v_mul_f32_e32 v3, 0xbfb8aa3b, v3
	v_add_f32_e32 v2, 1.0, v2
	v_rcp_f32_e32 v2, v2
	v_fmac_f32_e32 v16, v80, v145
	v_mul_f32_e32 v18, v69, v80
	v_exp_f32_e32 v3, v3
	v_mul_f32_e32 v2, v144, v2
	v_exp_f32_e32 v80, v2
	v_mul_f32_e32 v69, v150, v0
	v_add_f32_e32 v2, 1.0, v3
	v_sub_f32_e32 v0, 1.0, v17
	v_fma_f32 v3, -v80, v80, 1.0
	v_max_f32_e32 v3, 0, v3
	v_cvt_pk_f16_f32 v19, v0, v69
	v_rcp_f32_e32 v2, v2
	v_sqrt_f32_e32 v3, v3
	v_lshl_add_u64 v[0:1], v[180:181], 0, v[208:209]
	global_store_dword v[0:1], v19, off
	v_fmac_f32_e32 v69, v17, v16
	v_mul_f32_e32 v1, v17, v18
	v_add_f32_e32 v17, v75, v20
	v_mul_f32_e32 v0, v2, v3
	v_mul_f32_e32 v17, 0xbfb8aa3b, v17
	v_mul_f32_e32 v0, v151, v0
	v_sub_f32_e32 v2, 1.0, v80
	v_exp_f32_e32 v17, v17
	v_cvt_pk_f16_f32 v16, v2, v0
	v_lshl_add_u64 v[2:3], v[182:183], 0, v[208:209]
	global_store_dword v[2:3], v16, off
	v_add_f32_e32 v2, 1.0, v17
	v_rcp_f32_e32 v2, v2
	v_add_f32_e32 v3, v143, v4
	v_mul_f32_e32 v3, 0xbfb8aa3b, v3
	v_exp_f32_e32 v3, v3
	v_mul_f32_e32 v2, v144, v2
	v_exp_f32_e32 v18, v2
	v_add_f32_e32 v5, v143, v5
	v_add_f32_e32 v2, 1.0, v3
	v_rcp_f32_e32 v4, v2
	v_fma_f32 v2, -v18, v18, 1.0
	v_max_f32_e32 v2, 0, v2
	v_sqrt_f32_e32 v16, v2
	v_fmac_f32_e32 v0, v80, v69
	v_mul_f32_e32 v5, 0xbfb8aa3b, v5
	v_add_f32_e32 v6, v143, v6
	v_mul_f32_e32 v4, v4, v16
	v_mul_f32_e32 v19, v152, v4
	v_add_f32_e32 v4, v75, v21
	v_mul_f32_e32 v4, 0xbfb8aa3b, v4
	v_exp_f32_e32 v4, v4
	v_exp_f32_e32 v21, v5
	v_sub_f32_e32 v16, 1.0, v18
	v_cvt_pk_f16_f32 v20, v16, v19
	v_add_f32_e32 v4, 1.0, v4
	v_rcp_f32_e32 v4, v4
	v_mul_f32_e32 v6, 0xbfb8aa3b, v6
	v_exp_f32_e32 v6, v6
	v_mul_f32_e32 v4, v144, v4
	v_exp_f32_e32 v69, v4
	v_add_f32_e32 v16, 1.0, v21
	v_rcp_f32_e32 v16, v16
	v_fma_f32 v17, -v69, v69, 1.0
	v_max_f32_e32 v17, 0, v17
	v_sqrt_f32_e32 v17, v17
	v_lshl_add_u64 v[4:5], v[184:185], 0, v[208:209]
	global_store_dword v[4:5], v20, off
	v_add_f32_e32 v5, v75, v22
	v_mul_f32_e32 v5, 0xbfb8aa3b, v5
	v_mul_f32_e32 v4, v16, v17
	v_exp_f32_e32 v17, v5
	v_mul_f32_e32 v16, v4, v153
	v_sub_f32_e32 v4, 1.0, v69
	v_cvt_pk_f16_f32 v20, v4, v16
; DI float sigm(float x) { return __builtin_amdgcn_rcpf(1.0f + __builtin_amdgcn_exp2f(-x * LOG2E)); }
; DI void rnn_phase(LAS unsigned char* lds, bf16_t* P, const bf16_t* WaT, const bf16_t* WiT, const float* convw, const float* convb, const float* ba, const float* bi, const float* lam,
;                   f32x2* sums, unsigned* au, bool fin, int bx, int G, int tid, int wid, int lane) {
;     ...
;                 for (int q4 = 0; q4 < 4; ++q4) { const int i = 4 * g + q4, tok = 32 * tt + 8 * g + 4 * hl + q4;
;                     const float r = sigm(aR[i] + bac), ig = sigm(aI[i] + bic);
;                     const float a = __builtin_amdgcn_exp2f(k8c * r);
;                     const float uu_ = __builtin_amdgcn_sqrtf(fmaxf(1.0f - a * a, 0.f)) * ig * XC[tok * 64 + ch];
;                     { const h2_t pv = {(_Float16)(1.0f - a), (_Float16)uu_}; au[(rowbase + tok) * D + ch0 + ch] = __builtin_bit_cast(unsigned, pv); }
;                     H = a * H + uu_; A *= a; }
	v_add_f32_e32 v17, 1.0, v17
	v_rcp_f32_e32 v17, v17
	v_add_f32_e32 v6, 1.0, v6
	v_mul_f32_e32 v17, v144, v17
	v_exp_f32_e32 v17, v17
	v_rcp_f32_e32 v6, v6
	v_lshl_add_u64 v[4:5], v[186:187], 0, v[208:209]
	global_store_dword v[4:5], v20, off
	v_fma_f32 v21, -v17, v17, 1.0
	v_max_f32_e32 v21, 0, v21
	v_sqrt_f32_e32 v21, v21
	v_add_f32_e32 v5, v75, v23
	v_mul_f32_e32 v5, 0xbfb8aa3b, v5
	v_add_f32_e32 v7, v143, v7
	v_mul_f32_e32 v4, v6, v21
	v_exp_f32_e32 v6, v5
	v_mul_f32_e32 v7, 0xbfb8aa3b, v7
	v_exp_f32_e32 v7, v7
	v_fmac_f32_e32 v19, 0, v18
	v_add_f32_e32 v6, 1.0, v6
	v_rcp_f32_e32 v6, v6
	v_fmac_f32_e32 v16, v69, v19
	v_mul_f32_e32 v19, v4, v154
	v_sub_f32_e32 v4, 1.0, v17
	v_mul_f32_e32 v6, v144, v6
	v_exp_f32_e32 v21, v6
	v_add_f32_e32 v6, 1.0, v7
	v_cvt_pk_f16_f32 v20, v4, v19
	v_fma_f32 v7, -v21, v21, 1.0
	v_max_f32_e32 v7, 0, v7
	v_rcp_f32_e32 v6, v6
	v_sqrt_f32_e32 v7, v7
	v_mul_f32_e32 v18, v18, v69
	v_lshl_add_u64 v[4:5], v[188:189], 0, v[208:209]
	global_store_dword v[4:5], v20, off
	v_fmac_f32_e32 v19, v17, v16
	v_mul_f32_e32 v5, v17, v18
	v_add_f32_e32 v17, v75, v24
	v_mul_f32_e32 v4, v6, v7
	v_mul_f32_e32 v17, 0xbfb8aa3b, v17
	v_mul_f32_e32 v4, v4, v155
	v_sub_f32_e32 v6, 1.0, v21
	v_exp_f32_e32 v17, v17
	v_cvt_pk_f16_f32 v16, v6, v4
	v_lshl_add_u64 v[6:7], v[190:191], 0, v[208:209]
	global_store_dword v[6:7], v16, off
	v_add_f32_e32 v6, 1.0, v17
	v_rcp_f32_e32 v6, v6
	v_add_f32_e32 v7, v143, v8
	v_mul_f32_e32 v7, 0xbfb8aa3b, v7
	v_exp_f32_e32 v7, v7
	v_mul_f32_e32 v6, v144, v6
	v_exp_f32_e32 v18, v6
	v_mul_f32_e32 v3, v80, v1
	v_add_f32_e32 v6, 1.0, v7
	v_rcp_f32_e32 v8, v6
	v_fma_f32 v6, -v18, v18, 1.0
	v_max_f32_e32 v6, 0, v6
	v_sqrt_f32_e32 v16, v6
	v_fmac_f32_e32 v4, v21, v19
	v_mul_f32_e32 v7, v21, v5
	v_add_f32_e32 v9, v143, v9
	v_mul_f32_e32 v8, v8, v16
	ds_read_b32 v16, v135
	ds_read_b32 v19, v136
	ds_read_b32 v20, v137
	ds_read_b32 v21, v138
	ds_read_b32 v22, v139
	ds_read_b32 v23, v140
	ds_read_b32 v24, v141
	ds_read_b32 v69, v142
	s_waitcnt lgkmcnt(0)
; DI float sigm(float x) { return __builtin_amdgcn_rcpf(1.0f + __builtin_amdgcn_exp2f(-x * LOG2E)); }
; DI void rnn_phase(LAS unsigned char* lds, bf16_t* P, const bf16_t* WaT, const bf16_t* WiT, const float* convw, const float* convb, const float* ba, const float* bi, const float* lam,
;                   f32x2* sums, unsigned* au, bool fin, int bx, int G, int tid, int wid, int lane) {
;     ...
;                 for (int q4 = 0; q4 < 4; ++q4) { const int i = 4 * g + q4, tok = 32 * tt + 8 * g + 4 * hl + q4;
;                     const float r = sigm(aR[i] + bac), ig = sigm(aI[i] + bic);
;                     const float a = __builtin_amdgcn_exp2f(k8c * r);
;                     const float uu_ = __builtin_amdgcn_sqrtf(fmaxf(1.0f - a * a, 0.f)) * ig * XC[tok * 64 + ch];
;                     { const h2_t pv = {(_Float16)(1.0f - a), (_Float16)uu_}; au[(rowbase + tok) * D + ch0 + ch] = __builtin_bit_cast(unsigned, pv); }
;                     H = a * H + uu_; A *= a; }
;                 const float pA = __shfl_xor(A, 32), pH = __shfl_xor(H, 32);
;                 const float fA = hl ? pA : A, fH = hl ? pH : H, sA = hl ? A : pA, sH = hl ? H : pH;
;                 Ht = fA * Ht + fH; At *= fA; Ht = sA * Ht + sH; At *= sA;
;             }
;             if (hl == 0) { SG[tt * 64 + ch] = At; SG[256 + tt * 64 + ch] = Ht; }
	v_mul_f32_e32 v80, v8, v16
	v_add_f32_e32 v8, v75, v25
	v_mul_f32_e32 v8, 0xbfb8aa3b, v8
	v_exp_f32_e32 v8, v8
	v_mul_f32_e32 v9, 0xbfb8aa3b, v9
	v_exp_f32_e32 v145, v9
	v_sub_f32_e32 v16, 1.0, v18
	v_add_f32_e32 v8, 1.0, v8
	v_rcp_f32_e32 v8, v8
	v_cvt_pk_f16_f32 v25, v16, v80
	v_add_f32_e32 v10, v143, v10
	v_mul_f32_e32 v8, v144, v8
	v_exp_f32_e32 v146, v8
	v_add_f32_e32 v16, 1.0, v145
	v_rcp_f32_e32 v16, v16
	v_fma_f32 v17, -v146, v146, 1.0
	v_max_f32_e32 v17, 0, v17
	v_sqrt_f32_e32 v17, v17
	v_lshl_add_u64 v[8:9], v[192:193], 0, v[208:209]
	global_store_dword v[8:9], v25, off
	v_add_f32_e32 v9, v75, v26
	v_mul_f32_e32 v9, 0xbfb8aa3b, v9
	v_mul_f32_e32 v8, v16, v17
	v_exp_f32_e32 v17, v9
	v_mul_f32_e32 v10, 0xbfb8aa3b, v10
	v_exp_f32_e32 v10, v10
	v_mul_f32_e32 v16, v8, v19
	v_add_f32_e32 v17, 1.0, v17
	v_rcp_f32_e32 v17, v17
	v_sub_f32_e32 v8, 1.0, v146
	v_cvt_pk_f16_f32 v19, v8, v16
	v_mul_f32_e32 v17, v144, v17
	v_exp_f32_e32 v17, v17
	v_add_f32_e32 v10, 1.0, v10
	v_rcp_f32_e32 v10, v10
	v_fma_f32 v25, -v17, v17, 1.0
	v_max_f32_e32 v25, 0, v25
	v_sqrt_f32_e32 v25, v25
	v_lshl_add_u64 v[8:9], v[194:195], 0, v[208:209]
	global_store_dword v[8:9], v19, off
	v_add_f32_e32 v9, v75, v27
	v_mul_f32_e32 v9, 0xbfb8aa3b, v9
	v_mul_f32_e32 v8, v10, v25
	v_exp_f32_e32 v10, v9
	v_add_f32_e32 v11, v143, v11
	v_mul_f32_e32 v11, 0xbfb8aa3b, v11
	v_exp_f32_e32 v11, v11
	v_add_f32_e32 v10, 1.0, v10
	v_rcp_f32_e32 v10, v10
	v_mul_f32_e32 v19, v8, v20
	v_sub_f32_e32 v8, 1.0, v17
	v_cvt_pk_f16_f32 v20, v8, v19
	v_mul_f32_e32 v10, v144, v10
	v_exp_f32_e32 v25, v10
	v_add_f32_e32 v10, 1.0, v11
	v_rcp_f32_e32 v10, v10
	v_fma_f32 v11, -v25, v25, 1.0
	v_max_f32_e32 v11, 0, v11
	v_sqrt_f32_e32 v11, v11
	v_fmac_f32_e32 v80, 0, v18
	v_fmac_f32_e32 v16, v146, v80
	v_mul_f32_e32 v18, v18, v146
	v_lshl_add_u64 v[8:9], v[196:197], 0, v[208:209]
	global_store_dword v[8:9], v20, off
	v_fmac_f32_e32 v19, v17, v16
	v_mul_f32_e32 v9, v17, v18
	v_add_f32_e32 v17, v75, v28
	v_mul_f32_e32 v8, v10, v11
	v_mul_f32_e32 v17, 0xbfb8aa3b, v17
	v_mul_f32_e32 v8, v8, v21
	v_sub_f32_e32 v10, 1.0, v25
	v_exp_f32_e32 v17, v17
	v_cvt_pk_f16_f32 v16, v10, v8
	v_lshl_add_u64 v[10:11], v[198:199], 0, v[208:209]
	global_store_dword v[10:11], v16, off
	v_add_f32_e32 v10, 1.0, v17
	v_rcp_f32_e32 v10, v10
	v_add_f32_e32 v11, v143, v12
	v_mul_f32_e32 v11, 0xbfb8aa3b, v11
	v_exp_f32_e32 v11, v11
	v_mul_f32_e32 v10, v144, v10
	v_exp_f32_e32 v18, v10
	v_fmac_f32_e32 v8, v25, v19
	v_add_f32_e32 v10, 1.0, v11
	v_rcp_f32_e32 v12, v10
	v_fma_f32 v10, -v18, v18, 1.0
	v_max_f32_e32 v10, 0, v10
	v_sqrt_f32_e32 v16, v10
	v_add_f32_e32 v13, v143, v13
	v_mul_f32_e32 v13, 0xbfb8aa3b, v13
	v_exp_f32_e32 v21, v13
	v_mul_f32_e32 v12, v12, v16
	v_mul_f32_e32 v19, v12, v22
	v_add_f32_e32 v12, v75, v29
	v_mul_f32_e32 v12, 0xbfb8aa3b, v12
	v_exp_f32_e32 v12, v12
	v_sub_f32_e32 v16, 1.0, v18
	v_cvt_pk_f16_f32 v20, v16, v19
	v_add_f32_e32 v12, 1.0, v12
	v_rcp_f32_e32 v12, v12
	v_fmac_f32_e32 v19, 0, v18
	v_add_f32_e32 v14, v143, v14
	v_mul_f32_e32 v14, 0xbfb8aa3b, v14
	v_mul_f32_e32 v12, v144, v12
	v_exp_f32_e32 v22, v12
	v_add_f32_e32 v16, 1.0, v21
	v_rcp_f32_e32 v16, v16
	v_fma_f32 v17, -v22, v22, 1.0
	v_max_f32_e32 v17, 0, v17
	v_sqrt_f32_e32 v17, v17
	v_lshl_add_u64 v[12:13], v[200:201], 0, v[208:209]
	global_store_dword v[12:13], v20, off
	v_add_f32_e32 v13, v75, v30
	v_mul_f32_e32 v12, v16, v17
	v_mul_f32_e32 v13, 0xbfb8aa3b, v13
	v_mul_f32_e32 v16, v12, v23
	v_sub_f32_e32 v12, 1.0, v22
	v_exp_f32_e32 v17, v13
	v_cvt_pk_f16_f32 v20, v12, v16
	v_lshl_add_u64 v[12:13], v[202:203], 0, v[208:209]
	v_add_f32_e32 v17, 1.0, v17
	global_store_dword v[12:13], v20, off
	v_add_f32_e32 v13, v75, v31
	v_rcp_f32_e32 v17, v17
	v_mul_f32_e32 v13, 0xbfb8aa3b, v13
	v_fmac_f32_e32 v16, v22, v19
	v_exp_f32_e32 v19, v13
	v_mul_f32_e32 v17, v144, v17
	v_exp_f32_e32 v17, v17
	v_exp_f32_e32 v14, v14
	v_add_f32_e32 v19, 1.0, v19
	v_rcp_f32_e32 v19, v19
	v_fma_f32 v21, -v17, v17, 1.0
	v_add_f32_e32 v14, 1.0, v14
	v_max_f32_e32 v21, 0, v21
	v_add_f32_e32 v15, v143, v15
	v_mul_f32_e32 v19, v144, v19
	v_rcp_f32_e32 v14, v14
	v_sqrt_f32_e32 v21, v21
	v_mul_f32_e32 v15, 0xbfb8aa3b, v15
	v_exp_f32_e32 v19, v19
	v_exp_f32_e32 v15, v15
	v_mul_f32_e32 v12, v14, v21
	v_mul_f32_e32 v14, v12, v24
	v_fma_f32 v21, -v19, v19, 1.0
	v_add_f32_e32 v15, 1.0, v15
	v_max_f32_e32 v21, 0, v21
	v_sub_f32_e32 v12, 1.0, v17
	v_rcp_f32_e32 v15, v15
	v_sqrt_f32_e32 v21, v21
	v_cvt_pk_f16_f32 v20, v12, v14
	v_lshl_add_u64 v[12:13], v[204:205], 0, v[208:209]
	v_mul_f32_e32 v18, v18, v22
	global_store_dword v[12:13], v20, off
	v_mul_f32_e32 v12, v15, v21
	v_fmac_f32_e32 v14, v17, v16
	v_mul_f32_e32 v13, v17, v18
	v_mul_f32_e32 v12, v12, v69
	v_sub_f32_e32 v15, 1.0, v19
	v_mul_f32_e32 v11, v25, v9
	v_cvt_pk_f16_f32 v18, v15, v12
	v_fmac_f32_e32 v12, v19, v14
	v_mul_f32_e32 v15, v19, v13
	ds_bpermute_b32 v2, v123, v3
	ds_bpermute_b32 v1, v123, v0
	ds_bpermute_b32 v6, v123, v7
	ds_bpermute_b32 v5, v123, v4
	ds_bpermute_b32 v10, v123, v11
	ds_bpermute_b32 v9, v123, v8
	ds_bpermute_b32 v13, v123, v15
	ds_bpermute_b32 v14, v123, v12
	v_lshl_add_u64 v[16:17], v[206:207], 0, v[208:209]
	global_store_dword v[16:17], v18, off
	s_and_saveexec_b64 s[38:39], s[40:41]
	s_cbranch_execz .LBB0_362
	v_fmac_f32_e32 v0, 0, v3
	s_waitcnt lgkmcnt(0)
	v_mul_f32_e32 v16, v3, v2
	v_fmac_f32_e32 v1, v0, v2
	v_mul_f32_e32 v16, v7, v16
	v_fmac_f32_e32 v4, v7, v1
	v_mul_f32_e32 v16, v16, v6
	v_fmac_f32_e32 v5, v4, v6
	v_mul_f32_e32 v16, v11, v16
	v_fmac_f32_e32 v8, v11, v5
	v_mul_f32_e32 v16, v16, v10
	v_fmac_f32_e32 v9, v8, v10
	v_mul_f32_e32 v16, v15, v16
	v_fmac_f32_e32 v12, v15, v9
	v_mul_f32_e32 v16, v16, v13
	v_fmac_f32_e32 v14, v12, v13
	ds_write2st64_b32 v124, v16, v14 offset1:4
